# speedup vs baseline: 1.0051x; 1.0015x over previous
; DEVI void partialSM(f32x16& p0, f32x16& p1, float& m_reg, float& mn, float& alpha) {
;     ...
;   for (int r = 0; r < 16; ++r) p0[r] = fmaf(p0[r], C, mnC);
; #pragma unroll
;   for (int r = 0; r < 16; ++r) p1[r] = fmaf(p1[r], C, mnC);
; #pragma unroll
;   for (int r = 0; r < 16; ++r) p0[r] = __builtin_amdgcn_exp2f(p0[r]);
; }
; DEVI void finishSM(f32x16& p0, f32x16& p1, float alpha, float& l_reg, bf16x8& pa0, bf16x8& pa1, bf16x8& pa2, bf16x8& pa3) {
; #pragma unroll
;   for (int r = 0; r < 16; ++r) p1[r] = __builtin_amdgcn_exp2f(p1[r]);
;   float ps = 0;
; #pragma unroll
;   for (int r = 0; r < 16; ++r) ps += p0[r];
; #pragma unroll
;   for (int r = 0; r < 16; ++r) ps += p1[r];
;   { auto rr = __builtin_amdgcn_permlane32_swap(__float_as_uint(ps), __float_as_uint(ps), false, false);
;     ps = __uint_as_float(rr[0]) + __uint_as_float(rr[1]); }
;   l_reg = l_reg * alpha + ps;
;     ...
;   PK4(p0, 0, pa0); PK4(p0, 8, pa1); PK4(p1, 0, pa2); PK4(p1, 8, pa3);
; DEVI void qkt(f32x16& p0, f32x16& p1, const char* Ks, const char* Rs, const bf16x8* qr, const char* Qrs, int r32, int hi) {
;   p0 = f32x16{}; p1 = f32x16{};
; #pragma unroll
;   for (int d0 = 0; d0 < 8; ++d0) { int cb = (d0 * 16 + hi * 8) * 2;
;     bf16x8 b0 = *reinterpret_cast<const bf16x8*>(Ks + KSWZ(r32, cb));
;     bf16x8 b1 = *reinterpret_cast<const bf16x8*>(Ks + KSWZ(32 + r32, cb));
;     p0 = __builtin_amdgcn_mfma_f32_32x32x16_bf16(b0, qr[d0], p0, 0, 0, 0);
;     p1 = __builtin_amdgcn_mfma_f32_32x32x16_bf16(b1, qr[d0], p1, 0, 0, 0); }
.LBB0_985:
	v_cndmask_b32_e64 v222, v140, v222, s[8:9]
	v_mul_f32_e32 v152, 0xbdd53b94, v222
	v_fmamk_f32 v66, v66, 0x3dd53b94, v152
	v_fmamk_f32 v67, v67, 0x3dd53b94, v152
	v_exp_f32_e32 v141, v66
	v_add_u32_e32 v66, 0x40000, v168
	v_fmamk_f32 v68, v68, 0x3dd53b94, v152
	v_exp_f32_e32 v236, v67
	v_fmamk_f32 v69, v69, 0x3dd53b94, v152
	v_exp_f32_e32 v237, v68
	v_add_u32_e32 v68, 0x60000, v168
	v_fmamk_f32 v128, v64, 0x3dd53b94, v152
	v_exp_f32_e32 v238, v69
	v_exp_f32_e32 v140, v128
	global_load_dwordx4 v[128:131], v66, s[36:37] offset:3072
	v_add_u32_e32 v66, 0x2000, v166
	global_load_dwordx4 v[132:135], v68, s[36:37] offset:3072
	global_load_dwordx4 v[136:139], v66, s[36:37] offset:3072
	v_fmamk_f32 v74, v74, 0x3dd53b94, v152
	v_fmamk_f32 v75, v75, 0x3dd53b94, v152
	v_exp_f32_e32 v228, v74
	v_exp_f32_e32 v229, v75
	v_fmamk_f32 v65, v65, 0x3dd53b94, v152
	v_fmamk_f32 v70, v70, 0x3dd53b94, v152
	v_fmamk_f32 v71, v71, 0x3dd53b94, v152
	v_fmamk_f32 v72, v72, 0x3dd53b94, v152
	v_fmamk_f32 v73, v73, 0x3dd53b94, v152
	v_fmamk_f32 v76, v76, 0x3dd53b94, v152
	v_fmamk_f32 v77, v77, 0x3dd53b94, v152
	v_fmamk_f32 v78, v78, 0x3dd53b94, v152
	v_fmamk_f32 v79, v79, 0x3dd53b94, v152
	v_fmamk_f32 v64, v80, 0x3dd53b94, v152
	v_fmamk_f32 v80, v81, 0x3dd53b94, v152
	v_fmamk_f32 v241, v82, 0x3dd53b94, v152
	v_fmamk_f32 v145, v83, 0x3dd53b94, v152
	v_fmamk_f32 v144, v84, 0x3dd53b94, v152
	v_fmamk_f32 v143, v85, 0x3dd53b94, v152
	v_fmamk_f32 v142, v86, 0x3dd53b94, v152
	v_fmamk_f32 v239, v87, 0x3dd53b94, v152
	v_fmamk_f32 v154, v88, 0x3dd53b94, v152
	v_fmamk_f32 v150, v89, 0x3dd53b94, v152
	v_fmamk_f32 v146, v90, 0x3dd53b94, v152
	v_fmamk_f32 v147, v91, 0x3dd53b94, v152
	v_fmamk_f32 v148, v92, 0x3dd53b94, v152
	v_exp_f32_e32 v240, v65
	v_exp_f32_e32 v234, v70
	v_exp_f32_e32 v235, v71
	v_exp_f32_e32 v232, v72
	v_exp_f32_e32 v233, v73
	v_exp_f32_e32 v230, v76
	v_exp_f32_e32 v231, v77
	v_exp_f32_e32 v153, v78
	v_exp_f32_e32 v155, v79
	v_fmamk_f32 v149, v93, 0x3dd53b94, v152
	v_fmamk_f32 v151, v94, 0x3dd53b94, v152
	v_fmac_f32_e32 v152, 0x3dd53b94, v95
	s_waitcnt lgkmcnt(0)
	s_barrier
	ds_read_b128 v[66:69], v187 offset:32768
	v_add_f32_e32 v65, 0, v140
	v_add_f32_e32 v65, v240, v65
	v_add_f32_e32 v81, v141, v65
	v_exp_f32_e32 v209, v64
	s_cmp_eq_u32 s4, s2
	s_cselect_b64 vcc, -1, 0
	s_waitcnt lgkmcnt(0)
	v_mfma_f32_32x32x16_bf16 v[64:79], v[66:69], v[96:99], 0
	ds_read_b128 v[82:85], v187 offset:40960
	v_add_f32_e32 v81, v236, v81
	v_add_f32_e32 v81, v237, v81
	v_add_f32_e32 v210, v238, v81
	v_exp_f32_e32 v211, v80
	s_waitcnt lgkmcnt(0)
	v_mfma_f32_32x32x16_bf16 v[80:95], v[82:85], v[96:99], 0
	ds_read_b128 v[170:173], v188 offset:32768
	v_add_f32_e32 v210, v234, v210
	v_add_f32_e32 v210, v235, v210
	v_add_f32_e32 v210, v232, v210
	v_exp_f32_e32 v212, v241
	s_waitcnt lgkmcnt(0)
	v_mfma_f32_32x32x16_bf16 v[64:79], v[170:173], v[100:103], v[64:79]
	ds_read_b128 v[170:173], v188 offset:40960
	v_add_f32_e32 v210, v233, v210
	v_add_f32_e32 v210, v228, v210
	v_add_f32_e32 v210, v229, v210
	v_exp_f32_e32 v214, v145
	s_waitcnt lgkmcnt(0)
	v_mfma_f32_32x32x16_bf16 v[80:95], v[170:173], v[100:103], v[80:95]
	ds_read_b128 v[170:173], v189 offset:32768
	v_add_f32_e32 v145, v230, v210
	v_add_f32_e32 v145, v231, v145
	v_add_f32_e32 v145, v153, v145
	v_exp_f32_e32 v210, v144
	s_waitcnt lgkmcnt(0)
	v_mfma_f32_32x32x16_bf16 v[64:79], v[170:173], v[104:107], v[64:79]
	ds_read_b128 v[170:173], v189 offset:40960
	v_add_f32_e32 v144, v155, v145
	v_add_f32_e32 v144, v209, v144
	v_add_f32_e32 v144, v211, v144
	v_exp_f32_e32 v215, v143
	s_waitcnt lgkmcnt(0)
	v_mfma_f32_32x32x16_bf16 v[80:95], v[170:173], v[104:107], v[80:95]
	ds_read_b128 v[170:173], v190 offset:32768
	v_add_f32_e32 v143, v212, v144
	v_add_f32_e32 v143, v214, v143
	v_add_f32_e32 v216, v210, v143
	v_exp_f32_e32 v217, v142
	s_waitcnt lgkmcnt(0)
	v_mfma_f32_32x32x16_bf16 v[64:79], v[170:173], v[108:111], v[64:79]
	ds_read_b128 v[142:145], v190 offset:40960
	v_add_f32_e32 v170, v215, v216
	v_cvt_pk_bf16_f32 v140, v140, v240
	v_add_f32_e32 v216, v217, v170
	v_exp_f32_e32 v218, v239
	s_waitcnt lgkmcnt(0)
	v_mfma_f32_32x32x16_bf16 v[80:95], v[142:145], v[108:111], v[80:95]
	ds_read_b128 v[170:173], v191 offset:32768
	v_cvt_pk_bf16_f32 v141, v141, v236
	v_cvt_pk_bf16_f32 v142, v237, v238
	v_add_f32_e32 v143, v218, v216
	v_exp_f32_e32 v154, v154
	s_waitcnt lgkmcnt(0)
	v_mfma_f32_32x32x16_bf16 v[64:79], v[170:173], v[112:115], v[64:79]
	ds_read_b128 v[170:173], v191 offset:40960
	v_add_f32_e32 v144, v154, v143
	v_cvt_pk_bf16_f32 v143, v234, v235
	v_permlane32_swap_b32_e32 v140, v142
	v_exp_f32_e32 v216, v150
	s_waitcnt lgkmcnt(0)
	v_mfma_f32_32x32x16_bf16 v[80:95], v[170:173], v[112:115], v[80:95]
	ds_read_b128 v[170:173], v192 offset:32768
	v_add_f32_e32 v145, v216, v144
	v_permlane32_swap_b32_e32 v141, v143
	v_cvt_pk_bf16_f32 v144, v232, v233
	v_exp_f32_e32 v219, v146
	s_waitcnt lgkmcnt(0)
	v_mfma_f32_32x32x16_bf16 v[64:79], v[170:173], v[116:119], v[64:79]
	ds_read_b128 v[170:173], v192 offset:40960
	v_add_f32_e32 v150, v219, v145
	v_cvt_pk_bf16_f32 v145, v228, v229
	v_cvt_pk_bf16_f32 v146, v230, v231
	v_exp_f32_e32 v236, v147
	s_waitcnt lgkmcnt(0)
	v_mfma_f32_32x32x16_bf16 v[80:95], v[170:173], v[116:119], v[80:95]
	ds_read_b128 v[170:173], v193 offset:32768
	v_add_f32_e32 v150, v236, v150
	v_cvt_pk_bf16_f32 v147, v153, v155
	v_permlane32_swap_b32_e32 v144, v146
	v_exp_f32_e32 v155, v148
	s_waitcnt lgkmcnt(0)
	v_mfma_f32_32x32x16_bf16 v[64:79], v[170:173], v[120:123], v[64:79]
	ds_read_b128 v[170:173], v193 offset:40960
	v_add_f32_e32 v150, v155, v150
	v_permlane32_swap_b32_e32 v145, v147
	v_cvt_pk_bf16_f32 v148, v209, v211
	v_exp_f32_e32 v209, v149
	s_waitcnt lgkmcnt(0)
; #define SBAR() __builtin_amdgcn_sched_barrier(0)
; #define SGB_QK() _Pragma("unroll") for (int g_ = 0; g_ < 24; ++g_) { __builtin_amdgcn_sched_group_barrier(0x008, 1, 0); __builtin_amdgcn_sched_group_barrier(0x100, 1, 0); \
;     __builtin_amdgcn_sched_group_barrier(0x002, 3, 0); __builtin_amdgcn_sched_group_barrier(0x400, 1, 0); }
; #define SLOAD_V(k0) do { const char* vb_ = (const char*)VTh + (size_t)(k0) * 2; const char* vb2_ = vb_ + vhalf;                \
;     vs0 = *reinterpret_cast<const bf16x8*>(vb_ + vo_v); vs1 = *reinterpret_cast<const bf16x8*>(vb2_ + vo_v); } while (0)
; #define SWRITE_KR(b) do { int kc = sc * 2; *(bf16x8*)(K_lds + (b) * SHM_K + KSWZ(sr, kc)) = ks0; *(bf16x8*)(K_lds + (b) * SHM_K + KSWZ(32 + sr, kc)) = ks1; \
;     *(bf16x8*)(R_lds + (b) * SHM_R + RSWZ(rr_, rc_ * 2)) = rs0; } while (0)
; #define SWRITE_V(b) do { *(bf16x8*)(V_lds + (b) * SHM_V + RSWZ(vd, vc * 16)) = vs0; *(bf16x8*)(V_lds + (b) * SHM_V + RSWZ(vd + 64, vc * 16)) = vs1; } while (0)
; #define SWAIT() asm volatile("s_waitcnt vmcnt(0)" ::: "memory")
; DEVI void partialSM(f32x16& p0, f32x16& p1, float& m_reg, float& mn, float& alpha) {
;     ...
;   float pmax = p0[0];
; #pragma unroll
;   for (int r = 1; r < 16; ++r) pmax = fmaxf(pmax, p0[r]);
; #pragma unroll
;   for (int r = 0; r < 16; ++r) pmax = fmaxf(pmax, p1[r]);
;   { auto rr = __builtin_amdgcn_permlane32_swap(__float_as_uint(pmax), __float_as_uint(pmax), false, false);
;     pmax = fmaxf(__uint_as_float(rr[0]), __uint_as_float(rr[1])); }
;   if (__builtin_expect(__all(pmax - m_reg <= ATHR / ASCALE), 1)) { mn = m_reg; alpha = 1.f; }
;   else { mn = fmaxf(m_reg, pmax); alpha = __builtin_amdgcn_exp2f((m_reg - mn) * C); m_reg = mn; }
; DEVI void attn_item(const u16* __restrict__ Qb, const u16* __restrict__ KNh, const u16* __restrict__ VTh, int Lpad, const u16* __restrict__ KRb,
;                     const u16* __restrict__ SZb, u16* __restrict__ AOb, int NT, char* lds, const int wid_s_) {
;     ...
;     if (j + 1 == NT - 2) mask_tile(pA0, pA1, true);
;     finishSM(pB0, pB1, alB, l_reg, pa0, pa1, pa2, pa3); SGB_QK(); SBAR();
;     SLOAD_V((j + 2) * 64); SBAR();
;     pv_d0(o, V_lds + SHM_V, r32, hi, pa0, pa1, pa2, pa3); partialSM(pA0, pA1, m_reg, mnA, alA);
;     SWRITE_KR(1);
;     __syncthreads(); SWAIT(); SWRITE_V(1);
	v_mfma_f32_32x32x16_bf16 v[80:95], v[170:173], v[120:123], v[80:95]
	ds_read_b128 v[170:173], v194 offset:32768
	v_add_f32_e32 v153, v209, v150
	v_cvt_pk_bf16_f32 v149, v212, v214
	v_cvt_pk_bf16_f32 v150, v210, v215
	v_exp_f32_e32 v210, v151
	s_waitcnt lgkmcnt(0)
	v_mfma_f32_32x32x16_bf16 v[64:79], v[170:173], v[124:127], v[64:79]
	ds_read_b128 v[170:173], v194 offset:40960
	v_add_f32_e32 v153, v210, v153
	v_cvt_pk_bf16_f32 v151, v217, v218
	v_permlane32_swap_b32_e32 v148, v150
	v_exp_f32_e32 v211, v152
	s_waitcnt lgkmcnt(0)
	v_mfma_f32_32x32x16_bf16 v[80:95], v[170:173], v[124:127], v[80:95]
	ds_read_b128 v[228:231], v195
	v_add_f32_e32 v170, v211, v153
	v_mov_b32_e32 v171, v170
	v_permlane32_swap_b32_e32 v149, v151
	ds_read_b128 v[232:235], v195 offset:4096
	v_permlane32_swap_b32_e32 v170, v171
	v_cvt_pk_bf16_f32 v152, v154, v216
	v_cvt_pk_bf16_f32 v153, v219, v236
	ds_read_b128 v[236:239], v196
	s_waitcnt lgkmcnt(0)
	v_mfma_f32_32x32x16_bf16 v[64:79], v[228:231], v[236:239], v[64:79]
	ds_read_b128 v[228:231], v197
	v_mfma_f32_32x32x16_bf16 v[80:95], v[232:235], v[236:239], v[80:95]
	ds_read_b128 v[240:243], v198
	ds_read_b128 v[232:235], v202
	ds_read_b128 v[236:239], v199 offset:4096
	s_waitcnt lgkmcnt(2)
	v_mfma_f32_32x32x16_bf16 v[64:79], v[228:231], v[240:243], v[64:79]
	ds_read_b128 v[228:231], v199
	ds_read_b128 v[244:247], v200
	s_waitcnt lgkmcnt(0)
	v_mfma_f32_32x32x16_bf16 v[64:79], v[228:231], v[244:247], v[64:79]
	ds_read_b128 v[228:231], v201
	s_waitcnt lgkmcnt(0)
	v_mfma_f32_32x32x16_bf16 v[64:79], v[228:231], v[232:235], v[64:79]
	ds_read_b128 v[226:229], v197 offset:4096
	s_waitcnt lgkmcnt(0)
	v_mfma_f32_32x32x16_bf16 v[80:95], v[226:229], v[240:243], v[80:95]
	ds_read_b128 v[240:243], v201 offset:4096
	v_cvt_pk_bf16_f32 v154, v155, v209
	v_cvt_pk_bf16_f32 v155, v210, v211
	s_nop 0
	v_permlane32_swap_b32_e32 v152, v154
	v_permlane32_swap_b32_e32 v153, v155
	v_mfma_f32_32x32x16_bf16 v[80:95], v[236:239], v[244:247], v[80:95]
	s_nop 1
	v_cndmask_b32_e32 v229, v72, v208, vcc
	v_cndmask_b32_e32 v227, v76, v208, vcc
	v_cndmask_b32_e32 v228, v73, v208, vcc
	s_waitcnt lgkmcnt(0)
	v_mfma_f32_32x32x16_bf16 v[80:95], v[240:243], v[232:235], v[80:95]
	s_nop 11
	v_cndmask_b32_e32 v73, v95, v208, vcc
	v_cndmask_b32_e32 v226, v74, v208, vcc
	v_cndmask_b32_e32 v172, v79, v208, vcc
	v_cndmask_b32_e32 v173, v78, v208, vcc
	v_cndmask_b32_e32 v223, v77, v208, vcc
	v_cndmask_b32_e32 v225, v75, v208, vcc
	v_cndmask_b32_e32 v72, v94, v208, vcc
	v_cndmask_b32_e32 v75, v93, v208, vcc
	v_cndmask_b32_e32 v74, v92, v208, vcc
	v_cndmask_b32_e32 v77, v91, v208, vcc
	v_cndmask_b32_e32 v76, v90, v208, vcc
	v_cndmask_b32_e32 v79, v89, v208, vcc
	v_cndmask_b32_e32 v78, v88, v208, vcc
	v_cndmask_b32_e32 v87, v87, v208, vcc
	v_cndmask_b32_e32 v86, v86, v208, vcc
	v_cndmask_b32_e32 v85, v85, v208, vcc
	v_cndmask_b32_e32 v84, v84, v208, vcc
	v_cndmask_b32_e32 v83, v83, v208, vcc
	v_cndmask_b32_e32 v82, v82, v208, vcc
	v_cndmask_b32_e32 v81, v81, v208, vcc
	v_cndmask_b32_e32 v80, v80, v208, vcc
	global_load_dwordx4 v[90:93], v162, s[36:37] offset:3456
	global_load_dwordx4 v[156:159], v164, s[36:37] offset:3456
	ds_read_b128 v[230:233], v177 offset:16384
	ds_read_b128 v[234:237], v161 offset:16384
	ds_read_b128 v[238:241], v180 offset:16384
	v_max_f32_e32 v88, v65, v65
	v_max_f32_e32 v89, v64, v64
	s_waitcnt lgkmcnt(2)
	v_mfma_f32_32x32x16_bf16 v[16:31], v[140:143], v[230:233], v[16:31]
	ds_read_b128 v[230:233], v177 offset:20480
	v_max_f32_e32 v88, v89, v88
	v_max3_f32 v88, v88, v66, v67
	v_max3_f32 v88, v88, v68, v69
	ds_read_b128 v[242:245], v179 offset:16384
	v_max3_f32 v88, v88, v70, v71
	v_max3_f32 v88, v88, v229, v228
	s_waitcnt lgkmcnt(1)
	v_mfma_f32_32x32x16_bf16 v[48:63], v[140:143], v[230:233], v[48:63]
	ds_read_b128 v[230:233], v177 offset:24576
	v_max3_f32 v88, v88, v226, v225
	v_max3_f32 v88, v88, v227, v223
	v_max3_f32 v88, v88, v173, v172
	v_max3_f32 v88, v88, v80, v81
	v_max3_f32 v88, v88, v82, v83
	v_max3_f32 v88, v88, v84, v85
	v_mfma_f32_32x32x16_bf16 v[16:31], v[144:147], v[234:237], v[16:31]
	ds_read_b128 v[234:237], v161 offset:20480
	v_max3_f32 v88, v88, v86, v87
	v_max3_f32 v88, v88, v78, v79
	v_max3_f32 v88, v88, v76, v77
	v_max3_f32 v88, v88, v74, v75
	v_max3_f32 v88, v88, v72, v73
	v_mov_b32_e32 v89, v88
	s_waitcnt lgkmcnt(1)
	v_mfma_f32_32x32x16_bf16 v[32:47], v[140:143], v[230:233], v[32:47]
	ds_read_b128 v[230:233], v177 offset:28672
	v_permlane32_swap_b32_e32 v88, v89
	v_max_f32_e32 v89, v89, v89
	v_max_f32_e32 v88, v88, v88
	v_max_f32_e32 v88, v88, v89
	v_sub_f32_e32 v89, v88, v222
	s_waitcnt lgkmcnt(1)
	v_mfma_f32_32x32x16_bf16 v[48:63], v[144:147], v[234:237], v[48:63]
	ds_read_b128 v[234:237], v161 offset:24576
	v_cmp_ge_f32_e32 vcc, s91, v89
	v_max_f32_e32 v89, v222, v222
	v_max_f32_e32 v89, v89, v88
	v_sub_f32_e32 v88, v222, v89
	v_mul_f32_e32 v88, 0x3dd53b94, v88
	v_exp_f32_e32 v88, v88
	s_waitcnt lgkmcnt(1)
	v_mfma_f32_32x32x16_bf16 v[0:15], v[140:143], v[230:233], v[0:15]
	s_cmp_eq_u64 vcc, exec
	s_cselect_b64 s[8:9], -1, 0
	v_cndmask_b32_e64 v88, v88, 1.0, s[8:9]
	v_cmp_gt_f32_e32 vcc, 1.0, v88
	v_mfma_f32_32x32x16_bf16 v[16:31], v[148:151], v[238:241], v[16:31]
	ds_read_b128 v[238:241], v180 offset:20480
	s_waitcnt lgkmcnt(1)
	v_mfma_f32_32x32x16_bf16 v[32:47], v[144:147], v[234:237], v[32:47]
	ds_read_b128 v[234:237], v161 offset:28672
	s_waitcnt lgkmcnt(1)
	v_mfma_f32_32x32x16_bf16 v[48:63], v[148:151], v[238:241], v[48:63]
	ds_read_b128 v[238:241], v180 offset:24576
	s_waitcnt lgkmcnt(1)
	v_mfma_f32_32x32x16_bf16 v[0:15], v[144:147], v[234:237], v[0:15]
	v_mfma_f32_32x32x16_bf16 v[16:31], v[152:155], v[242:245], v[16:31]
	ds_read_b128 v[242:245], v179 offset:20480
	s_waitcnt lgkmcnt(1)
	v_mfma_f32_32x32x16_bf16 v[32:47], v[148:151], v[238:241], v[32:47]
	ds_read_b128 v[238:241], v180 offset:28672
	s_waitcnt lgkmcnt(1)
	v_mfma_f32_32x32x16_bf16 v[48:63], v[152:155], v[242:245], v[48:63]
	ds_read_b128 v[242:245], v179 offset:24576
	s_waitcnt lgkmcnt(1)
	v_mfma_f32_32x32x16_bf16 v[0:15], v[148:151], v[238:241], v[0:15]
	s_waitcnt lgkmcnt(0)
	v_mfma_f32_32x32x16_bf16 v[32:47], v[152:155], v[242:245], v[32:47]
	ds_read_b128 v[242:245], v179 offset:28672
	s_waitcnt vmcnt(2)
	ds_write_b128 v184, v[128:131] offset:49152
	ds_write_b128 v184, v[132:135] offset:57344
	ds_write_b128 v203, v[136:139]
	s_waitcnt lgkmcnt(0)
	s_barrier
; #define SWRITE_V(b) do { *(bf16x8*)(V_lds + (b) * SHM_V + RSWZ(vd, vc * 16)) = vs0; *(bf16x8*)(V_lds + (b) * SHM_V + RSWZ(vd + 64, vc * 16)) = vs1; } while (0)
; #define SWAIT() asm volatile("s_waitcnt vmcnt(0)" ::: "memory")
; #define RESC(a) do { if (__any((a) < 1.f)) { if (hi == 0) al_l[r32] = (a); asm volatile("s_waitcnt lgkmcnt(0)" ::: "memory"); \
;     _Pragma("unroll") for (int d = 0; d < 4; ++d) _Pragma("unroll") for (int r = 0; r < 16; ++r) o[d][r] *= al_l[crow(r, hi)]; } } while (0)
; DEVI void attn_item(const u16* __restrict__ Qb, const u16* __restrict__ KNh, const u16* __restrict__ VTh, int Lpad, const u16* __restrict__ KRb,
;                     const u16* __restrict__ SZb, u16* __restrict__ AOb, int NT, char* lds, const int wid_s_) {
;     ...
;     __syncthreads(); SWAIT(); SWRITE_V(1);
;     RESC(alA); __syncthreads();
	v_mfma_f32_32x32x16_bf16 v[0:15], v[152:155], v[242:245], v[0:15]
	s_waitcnt vmcnt(0)
	ds_write_b128 v185, v[90:93] offset:16384
	ds_write_b128 v185, v[156:159] offset:24576
	s_cbranch_vccz .LBB0_989
	s_and_saveexec_b64 s[14:15], s[6:7]
	ds_write_b32 v181, v88 offset:128
	s_or_b64 exec, exec, s[14:15]
	s_waitcnt lgkmcnt(0)
	v_add_u32_e32 v94, v178, v160
	ds_read_b128 v[90:93], v94 offset:224
	ds_read_b128 v[128:131], v94 offset:192
	ds_read_b128 v[132:135], v94 offset:160
	ds_read_b128 v[136:139], v94 offset:128
	s_waitcnt lgkmcnt(3)
	v_pk_mul_f32 v[28:29], v[28:29], v[90:91]
	s_waitcnt lgkmcnt(2)
	v_pk_mul_f32 v[24:25], v[24:25], v[128:129]
	s_waitcnt lgkmcnt(1)
	v_pk_mul_f32 v[20:21], v[20:21], v[132:133]
	v_pk_mul_f32 v[30:31], v[30:31], v[92:93]
	v_pk_mul_f32 v[26:27], v[26:27], v[130:131]
	v_pk_mul_f32 v[22:23], v[22:23], v[134:135]
	s_waitcnt lgkmcnt(0)
	v_pk_mul_f32 v[18:19], v[18:19], v[138:139]
	v_pk_mul_f32 v[16:17], v[16:17], v[136:137]
	v_pk_mul_f32 v[60:61], v[60:61], v[90:91]
	v_pk_mul_f32 v[56:57], v[56:57], v[128:129]
	v_pk_mul_f32 v[52:53], v[52:53], v[132:133]
	v_pk_mul_f32 v[62:63], v[62:63], v[92:93]
	v_pk_mul_f32 v[58:59], v[58:59], v[130:131]
	v_pk_mul_f32 v[54:55], v[54:55], v[134:135]
	v_pk_mul_f32 v[50:51], v[50:51], v[138:139]
	v_pk_mul_f32 v[48:49], v[48:49], v[136:137]
	v_pk_mul_f32 v[44:45], v[44:45], v[90:91]
	v_pk_mul_f32 v[40:41], v[40:41], v[128:129]
	v_pk_mul_f32 v[36:37], v[36:37], v[132:133]
	v_pk_mul_f32 v[46:47], v[46:47], v[92:93]
	v_pk_mul_f32 v[42:43], v[42:43], v[130:131]
	v_pk_mul_f32 v[38:39], v[38:39], v[134:135]
	v_pk_mul_f32 v[34:35], v[34:35], v[138:139]
	v_pk_mul_f32 v[32:33], v[32:33], v[136:137]
	v_pk_mul_f32 v[12:13], v[12:13], v[90:91]
	v_pk_mul_f32 v[8:9], v[8:9], v[128:129]
	v_pk_mul_f32 v[4:5], v[4:5], v[132:133]
	v_pk_mul_f32 v[14:15], v[14:15], v[92:93]
	v_pk_mul_f32 v[10:11], v[10:11], v[130:131]
	v_pk_mul_f32 v[6:7], v[6:7], v[134:135]
	v_pk_mul_f32 v[2:3], v[2:3], v[138:139]
	v_pk_mul_f32 v[0:1], v[0:1], v[136:137]
